# three grid barriers replaced by release/acquire counters: P3||P4, P9||P10 (sample-row reductions on workgroups 64-127), P5->P7 (retention-state units publish, P7 acquires)
# speedup vs baseline: 1.0272x; 1.0132x over previous
.LBB0_375:
	s_or_b64 exec, exec, s[4:5]
	v_readlane_b32 s0, v255, 18
	s_cmpk_lt_i32 s0, 0x200
	s_cselect_b64 s[0:1], -1, 0
	v_writelane_b32 v255, s0, 19
	s_waitcnt lgkmcnt(0)
	v_mov_b32_e32 v0, v252
	v_readlane_b32 s92, v255, 18
	s_nop 1
	s_sub_i32 s92, s92, 0x200
	s_cmp_lt_u32 s92, 0x200
	s_cselect_b64 vcc, exec, 0
	v_writelane_b32 v255, s1, 20
	s_barrier
	s_cbranch_vccz .LBB0_420
	s_load_dwordx4 s[20:23], s[80:81], 0x48
	s_load_dwordx4 s[12:15], s[80:81], 0x0
	s_load_dwordx4 s[8:11], s[80:81], 0xc8
	v_lshlrev_b32_e32 v1, 2, v0
	v_and_b32_e32 v2, 0xfc, v1
	v_mov_b32_e32 v5, 0
	v_lshlrev_b32_e32 v4, 1, v2
	v_mbcnt_hi_u32_b32 v1, -1, v253
	s_waitcnt lgkmcnt(0)
	v_lshl_add_u64 v[6:7], s[10:11], 0, v[4:5]
	v_lshlrev_b32_e32 v4, 2, v2
	v_and_b32_e32 v3, 64, v1
	v_lshl_add_u64 v[8:9], s[10:11], 0, v[4:5]
	v_lshl_add_u64 v[36:37], s[20:21], 0, v[4:5]
	v_lshl_add_u64 v[38:39], s[8:9], 0, v[4:5]
	v_lshl_add_u64 v[40:41], s[22:23], 0, v[4:5]
	v_add_u32_e32 v3, 64, v3
	v_xor_b32_e32 v4, 1, v1
	v_cmp_lt_i32_e32 vcc, v4, v3
	s_cmp_lg_u64 s[22:23], 0
	s_mov_b32 s0, s92
	v_cndmask_b32_e32 v4, v1, v4, vcc
	v_lshlrev_b32_e32 v82, 2, v4
	v_xor_b32_e32 v4, 2, v1
	v_cmp_lt_i32_e32 vcc, v4, v3
	s_cselect_b64 s[4:5], -1, 0
	s_add_i32 s16, s0, 0x8000
	v_cndmask_b32_e32 v4, v1, v4, vcc
	v_lshlrev_b32_e32 v83, 2, v4
	v_xor_b32_e32 v4, 4, v1
	v_cmp_lt_i32_e32 vcc, v4, v3
	s_mov_b64 s[6:7], 0x1d600000
	v_lshl_add_u64 v[34:35], v[8:9], 0, s[6:7]
	v_cndmask_b32_e32 v4, v1, v4, vcc
	v_lshlrev_b32_e32 v84, 2, v4
	v_xor_b32_e32 v4, 8, v1
	v_cmp_lt_i32_e32 vcc, v4, v3
	s_mov_b64 s[6:7], 0x2f00000
	s_ashr_i32 s17, s16, 31
	v_cndmask_b32_e32 v4, v1, v4, vcc
	v_lshlrev_b32_e32 v85, 2, v4
	v_xor_b32_e32 v4, 16, v1
	v_cmp_lt_i32_e32 vcc, v4, v3
	v_lshl_add_u64 v[42:43], v[6:7], 0, s[6:7]
	s_lshl_b64 s[6:7], s[16:17], 11
	v_cndmask_b32_e32 v4, v1, v4, vcc
	v_lshlrev_b32_e32 v86, 2, v4
	v_xor_b32_e32 v4, 32, v1
	v_cmp_lt_i32_e32 vcc, v4, v3
	v_and_b32_e32 v3, 63, v0
	s_add_u32 s6, s10, s6
	v_cndmask_b32_e32 v1, v1, v4, vcc
	v_lshlrev_b32_e32 v4, 3, v3
	s_addc_u32 s7, s11, s7
	s_mov_b64 s[0:1], 0x7000000
	v_lshlrev_b32_e32 v87, 2, v1
	v_lshl_add_u64 v[0:1], s[6:7], 0, v[4:5]
	s_ashr_i32 s83, s82, 31
	v_lshl_add_u64 v[32:33], v[6:7], 0, s[0:1]
	v_lshl_add_u64 v[44:45], v[0:1], 0, s[0:1]
	s_lshl_b64 s[10:11], s[82:83], 11
	s_lshl_b64 s[0:1], s[16:17], 12
	s_add_u32 s0, s8, s0
	v_lshlrev_b32_e32 v4, 4, v3
	s_addc_u32 s1, s9, s1
	v_lshl_add_u64 v[0:1], s[0:1], 0, v[4:5]
	s_mov_b64 s[0:1], 0xc00
	s_mov_b32 s19, 0
	v_lshl_add_u64 v[46:47], v[0:1], 0, s[0:1]
	s_lshl_b64 s[20:21], s[82:83], 12
	v_lshlrev_b32_e32 v88, 2, v2
	v_mov_b32_e32 v89, 0x358637bd
	s_mov_b32 s0, 0xfbf00000
	s_mov_b32 s1, 0xfbf01000
	s_branch .LBB0_378

.LBB0_420:
	s_waitcnt vmcnt(0)
	v_readlane_b32 s4, v255, 6
	v_readlane_b32 s5, v255, 7
	s_barrier
	s_and_saveexec_b64 s[0:1], s[4:5]
	s_xor_b64 s[4:5], exec, s[0:1]
	s_cbranch_execz .LBB0_473
	s_cmp_lt_u32 s92, 0x200
	s_cbranch_scc0 .LBB0_473
	buffer_wbl2 sc1
	s_waitcnt vmcnt(0)
	v_readlane_b32 s6, v255, 3
	v_readlane_b32 s7, v255, 4
	v_mov_b32_e32 v0, 0
	v_mov_b32_e32 v1, 1
	s_nop 4
	global_atomic_add v0, v1, s[6:7] offset:36
	s_waitcnt vmcnt(0)

.LBB0_481:
	s_add_i32 s57, s57, 1
	s_cmp_lg_u32 s57, 5
	s_cbranch_scc1 .Lp4_noacq
	s_and_b32 s94, s2, 7
	s_cmp_lg_u32 s94, 7
	s_cbranch_scc1 .Lp4_noacq
	v_readlane_b32 s72, v255, 3
	v_readlane_b32 s73, v255, 4
	v_mov_b32_e32 v250, 0
	s_mov_b32 s95, 0
	s_nop 4
.Lp4_poll:
	global_load_dword v251, v250, s[72:73] offset:36 sc1
	s_waitcnt vmcnt(0)
	v_readfirstlane_b32 s94, v251
	s_cmp_ge_u32 s94, 64
	s_cbranch_scc1 .Lp4_acq
	s_add_u32 s95, s95, 1
	s_cmp_gt_u32 s95, 4000
	s_cbranch_scc1 .Lp4_acq
	s_sleep 2
	s_branch .Lp4_poll

.Lp4_noacq:
	s_mul_i32 s0, s57, s85
	s_mul_hi_u32 s1, s57, s84
	s_add_i32 s1, s1, s0
	s_mul_i32 s0, s57, s84
	s_add_u32 s36, s0, s2
	s_addc_u32 s37, s1, s3
	v_cmp_gt_i64_e32 vcc, s[36:37], v[196:197]
	v_cmp_lt_i64_e64 s[8:9], s[36:37], v[194:195]
	s_cbranch_vccnz .LBB0_487
	s_ashr_i32 s0, s36, 31
	s_lshr_b32 s0, s0, 29
	s_add_i32 s0, s36, s0
	s_and_b32 s1, s0, -8
	s_sub_i32 s1, s36, s1
	s_cmp_gt_i32 s1, 3
	s_mov_b64 s[30:31], -1
	s_cbranch_scc0 .LBB0_484
	s_mul_i32 s11, s1, 0xe3
	s_add_i32 s11, s11, 4
	s_mov_b64 s[30:31], 0

.LBB0_658:
	v_ashrrev_i32_e32 v179, 31, v178
	s_lshl_b32 s4, s10, 5
	s_ashr_i32 s5, s4, 31
	s_waitcnt vmcnt(35)
	v_lshlrev_b64 v[34:35], 7, v[178:179]
	v_lshl_add_u64 v[34:35], v[34:35], 0, s[4:5]
	v_lshlrev_b32_e32 v0, 2, v63
	v_lshl_add_u64 v[36:37], s[12:13], 0, v[0:1]
	v_lshl_or_b32 v34, v62, 2, v34
	s_lshl_b32 s24, s11, 2
	s_waitcnt vmcnt(34)
	v_lshlrev_b64 v[38:39], 9, v[34:35]
	v_lshl_add_u64 v[40:41], v[36:37], 0, s[24:25]
	s_waitcnt vmcnt(33)
	v_lshl_add_u64 v[42:43], v[40:41], 0, v[38:39]
	global_store_dword v[42:43], v2, off
	v_or_b32_e32 v42, 1, v34
	v_mov_b32_e32 v43, v35
	v_lshlrev_b64 v[42:43], 9, v[42:43]
	v_lshl_add_u64 v[44:45], v[40:41], 0, v[42:43]
	global_store_dword v[44:45], v3, off
	v_or_b32_e32 v2, 2, v34
	v_mov_b32_e32 v3, v35
	v_lshlrev_b64 v[2:3], 9, v[2:3]
	v_lshl_add_u64 v[44:45], v[40:41], 0, v[2:3]
	global_store_dword v[44:45], v4, off
	v_or_b32_e32 v44, 3, v34
	v_mov_b32_e32 v45, v35
	v_lshlrev_b64 v[44:45], 9, v[44:45]
	s_waitcnt vmcnt(35)
	v_lshl_add_u64 v[46:47], v[40:41], 0, v[44:45]
	global_store_dword v[46:47], v5, off
	v_or_b32_e32 v4, 8, v34
	v_mov_b32_e32 v5, v35
	v_lshlrev_b64 v[4:5], 9, v[4:5]
	v_lshl_add_u64 v[46:47], v[40:41], 0, v[4:5]
	global_store_dword v[46:47], v6, off
	v_or_b32_e32 v46, 9, v34
	v_mov_b32_e32 v47, v35
	v_lshlrev_b64 v[46:47], 9, v[46:47]
	v_lshl_add_u64 v[48:49], v[40:41], 0, v[46:47]
	global_store_dword v[48:49], v7, off
	v_or_b32_e32 v6, 10, v34
	v_mov_b32_e32 v7, v35
	v_lshlrev_b64 v[6:7], 9, v[6:7]
	v_lshl_add_u64 v[48:49], v[40:41], 0, v[6:7]
	global_store_dword v[48:49], v8, off
	v_or_b32_e32 v48, 11, v34
	v_mov_b32_e32 v49, v35
	v_lshlrev_b64 v[48:49], 9, v[48:49]
	v_lshl_add_u64 v[50:51], v[40:41], 0, v[48:49]
	global_store_dword v[50:51], v9, off
	v_or_b32_e32 v8, 16, v34
	v_mov_b32_e32 v9, v35
	v_lshlrev_b64 v[8:9], 9, v[8:9]
	v_lshl_add_u64 v[50:51], v[40:41], 0, v[8:9]
	global_store_dword v[50:51], v10, off
	v_or_b32_e32 v50, 17, v34
	v_mov_b32_e32 v51, v35
	v_lshlrev_b64 v[50:51], 9, v[50:51]
	v_lshl_add_u64 v[52:53], v[40:41], 0, v[50:51]
	global_store_dword v[52:53], v11, off
	v_or_b32_e32 v10, 18, v34
	v_mov_b32_e32 v11, v35
	v_lshlrev_b64 v[10:11], 9, v[10:11]
	v_lshl_add_u64 v[52:53], v[40:41], 0, v[10:11]
	global_store_dword v[52:53], v12, off
	v_or_b32_e32 v52, 19, v34
	v_mov_b32_e32 v53, v35
	v_lshlrev_b64 v[52:53], 9, v[52:53]
	v_lshl_add_u64 v[54:55], v[40:41], 0, v[52:53]
	global_store_dword v[54:55], v13, off
	v_or_b32_e32 v12, 24, v34
	v_mov_b32_e32 v13, v35
	v_lshlrev_b64 v[12:13], 9, v[12:13]
	v_lshl_add_u64 v[54:55], v[40:41], 0, v[12:13]
	global_store_dword v[54:55], v14, off
	v_or_b32_e32 v54, 25, v34
	v_mov_b32_e32 v55, v35
	v_lshlrev_b64 v[54:55], 9, v[54:55]
	v_lshl_add_u64 v[56:57], v[40:41], 0, v[54:55]
	global_store_dword v[56:57], v15, off
	v_or_b32_e32 v14, 26, v34
	v_mov_b32_e32 v15, v35
	v_or_b32_e32 v34, 27, v34
	v_lshlrev_b64 v[14:15], 9, v[14:15]
	v_lshlrev_b64 v[34:35], 9, v[34:35]
	v_lshl_add_u64 v[56:57], v[40:41], 0, v[14:15]
	v_lshl_add_u64 v[40:41], v[40:41], 0, v[34:35]
	s_lshl_b32 s24, s0, 7
	global_store_dword v[56:57], v16, off
	global_store_dword v[40:41], v17, off
	v_lshl_add_u64 v[16:17], v[36:37], 0, s[24:25]
	v_lshl_add_u64 v[2:3], v[16:17], 0, v[2:3]
	global_store_dword v[2:3], v20, off
	v_lshl_add_u64 v[2:3], v[16:17], 0, v[44:45]
	global_store_dword v[2:3], v21, off
	v_lshl_add_u64 v[2:3], v[16:17], 0, v[4:5]
	global_store_dword v[2:3], v22, off
	v_lshl_add_u64 v[2:3], v[16:17], 0, v[46:47]
	global_store_dword v[2:3], v23, off
	v_lshl_add_u64 v[2:3], v[16:17], 0, v[6:7]
	global_store_dword v[2:3], v24, off
	v_lshl_add_u64 v[2:3], v[16:17], 0, v[48:49]
	global_store_dword v[2:3], v25, off
	v_lshl_add_u64 v[2:3], v[16:17], 0, v[8:9]
	global_store_dword v[2:3], v26, off
	v_lshl_add_u64 v[2:3], v[16:17], 0, v[50:51]
	global_store_dword v[2:3], v27, off
	v_lshl_add_u64 v[2:3], v[16:17], 0, v[10:11]
	global_store_dword v[2:3], v28, off
	v_lshl_add_u64 v[2:3], v[16:17], 0, v[52:53]
	global_store_dword v[2:3], v29, off
	v_lshl_add_u64 v[2:3], v[16:17], 0, v[12:13]
	global_store_dword v[2:3], v30, off
	v_lshl_add_u64 v[2:3], v[16:17], 0, v[54:55]
	v_lshl_add_u64 v[36:37], v[16:17], 0, v[38:39]
	global_store_dword v[2:3], v31, off
	v_lshl_add_u64 v[2:3], v[16:17], 0, v[14:15]
	global_store_dword v[36:37], v18, off
	v_lshl_add_u64 v[36:37], v[16:17], 0, v[42:43]
	global_store_dword v[2:3], v32, off
	v_lshl_add_u64 v[2:3], v[16:17], 0, v[34:35]
	global_store_dword v[36:37], v19, off
	global_store_dword v[2:3], v33, off
	s_waitcnt vmcnt(0)
	s_barrier
	s_and_saveexec_b64 s[4:5], s[6:7]
	s_cbranch_execz .Lrs_p_skip
	buffer_wbl2 sc1
	s_waitcnt vmcnt(0)
	v_readlane_b32 s0, v255, 3
	v_readlane_b32 s1, v255, 4
	v_mov_b32_e32 v0, 0
	v_mov_b32_e32 v2, 1
	s_nop 4
	global_atomic_add v0, v2, s[0:1] offset:40
	s_waitcnt vmcnt(0)
.Lrs_p_skip:
	s_or_b64 exec, exec, s[4:5]
.LBB0_659:
	s_mov_b64 s[4:5], 0

.LBB0_665:
	s_or_b64 exec, exec, s[4:5]
	s_waitcnt lgkmcnt(0)
	s_barrier
	ds_read_b32 v178, v185
	s_movk_i32 s0, 0x45f
	s_mov_b64 s[4:5], -1
	s_waitcnt lgkmcnt(0)
	s_barrier
	v_cmp_lt_i32_e32 vcc, s0, v178
	s_cbranch_vccnz .LBB0_660
	v_cmp_lt_i32_e32 vcc, 31, v178
	s_cbranch_vccz .LBB0_748
	s_movk_i32 s0, 0x43f
	v_cmp_lt_u32_e32 vcc, s0, v178
	s_cbranch_vccz .LBB0_669
	v_and_b32_e32 v0, 3, v178
	v_cvt_f32_ubyte0_e32 v2, v0
	v_sub_f32_e32 v2, 0xc0a00000, v2
	v_cmp_gt_f32_e32 vcc, s51, v2
	s_and_b64 s[0:1], vcc, exec
	s_cselect_b32 s0, 0xffffffc0, 0
	v_cndmask_b32_e32 v3, 0, v187, vcc
	v_add_f32_e32 v2, v2, v3
	v_exp_f32_e32 v2, v2
	v_add_u32_e32 v20, 0xfffffbc0, v178
	v_mov_b32_e32 v4, v252
	v_ldexp_f32 v2, v2, s0
	v_sub_f32_e32 v2, 1.0, v2
	v_log_f32_e32 v98, v2
	v_lshlrev_b32_e32 v2, 4, v20
	v_and_b32_e32 v2, 0x7fffffc0, v2
	v_bfe_u32 v19, v4, 5, 1
	v_mul_f32_e32 v3, 0x42800000, v98
	v_cmp_gt_f32_e32 vcc, s51, v3
	s_and_b64 s[0:1], vcc, exec
	s_cselect_b32 s0, 0xffffffc0, 0
	v_cndmask_b32_e32 v3, 0, v187, vcc
	v_fmac_f32_e32 v3, 0x42800000, v98
	v_exp_f32_e32 v3, v3
	v_add_u32_e32 v2, 0x8000, v2
	v_ashrrev_i32_e32 v102, 4, v4
	v_readfirstlane_b32 s4, v4
	v_ldexp_f32 v18, v3, s0
	v_bfe_u32 v3, v4, 2, 2
	v_lshl_or_b32 v100, v19, 3, v3
	v_and_b32_e32 v3, 16, v4
	v_lshlrev_b32_e32 v5, 2, v4
	v_add_u32_e32 v8, v2, v102
	v_mov_b64_e32 v[6:7], s[18:19]
	v_and_b32_e32 v99, 31, v4
	v_and_or_b32 v101, v5, 12, v3
	s_ashr_i32 s1, s4, 7
	s_lshr_b32 s0, s4, 5
	v_mad_i64_i32 v[2:3], s[4:5], v8, s52, v[6:7]
	v_lshlrev_b32_e32 v0, 8, v0
	v_lshlrev_b32_e32 v4, 4, v4
	v_lshl_add_u64 v[2:3], v[2:3], 0, v[0:1]
	v_and_b32_e32 v84, 0xf0, v4
	v_mov_b32_e32 v85, v1
	v_lshl_add_u64 v[2:3], v[2:3], 0, v[84:85]
	global_load_dwordx4 v[14:17], v[2:3], off offset:1024
	s_nop 0
	global_load_dwordx4 v[2:5], v[2:3], off offset:2048
	v_add_u32_e32 v8, 32, v8
	v_mad_i64_i32 v[6:7], s[4:5], v8, s52, v[6:7]
	v_lshl_add_u64 v[6:7], v[6:7], 0, v[0:1]
	v_lshl_add_u64 v[6:7], v[6:7], 0, v[84:85]
	global_load_dwordx4 v[10:13], v[6:7], off offset:1024
	s_nop 0
	global_load_dwordx4 v[6:9], v[6:7], off offset:2048
	s_load_dwordx2 s[4:5], s[80:81], 0x10
	v_mov_b32_e32 v21, v1
	s_lshl_b32 s8, s1, 5
	v_lshlrev_b64 v[20:21], 7, v[20:21]
	s_ashr_i32 s9, s8, 31
	v_lshl_add_u64 v[28:29], v[20:21], 0, s[8:9]
	s_and_b32 s0, s0, 2
	v_lshlrev_b32_e32 v0, 2, v99
	v_lshl_or_b32 v28, v19, 2, v28
	s_waitcnt lgkmcnt(0)
	v_lshl_add_u64 v[66:67], s[4:5], 0, v[0:1]
	s_lshl_b32 s24, s0, 7
	v_or_b32_e32 v22, 1, v28
	v_mov_b32_e32 v23, v29
	v_or_b32_e32 v24, 2, v28
	v_mov_b32_e32 v25, v29
	v_or_b32_e32 v26, 3, v28
	v_mov_b32_e32 v27, v29
	v_lshl_add_u64 v[30:31], v[66:67], 0, s[24:25]
	v_lshlrev_b64 v[34:35], 9, v[28:29]
	v_lshlrev_b64 v[36:37], 9, v[22:23]
	v_lshlrev_b64 v[38:39], 9, v[24:25]
	v_lshlrev_b64 v[40:41], 9, v[26:27]
	v_or_b32_e32 v32, 8, v28
	v_mov_b32_e32 v33, v29
	v_or_b32_e32 v44, 9, v28
	v_mov_b32_e32 v45, v29
	v_or_b32_e32 v46, 10, v28
	v_mov_b32_e32 v47, v29
	v_or_b32_e32 v48, 11, v28
	v_mov_b32_e32 v49, v29
	v_lshl_add_u64 v[20:21], v[30:31], 0, v[34:35]
	v_lshl_add_u64 v[22:23], v[30:31], 0, v[36:37]
	v_lshl_add_u64 v[24:25], v[30:31], 0, v[38:39]
	v_lshl_add_u64 v[26:27], v[30:31], 0, v[40:41]
	v_lshlrev_b64 v[42:43], 9, v[32:33]
	v_lshlrev_b64 v[44:45], 9, v[44:45]
	v_lshlrev_b64 v[46:47], 9, v[46:47]
	v_lshlrev_b64 v[48:49], 9, v[48:49]
	v_lshl_add_u64 v[32:33], v[30:31], 0, v[42:43]
	v_lshl_add_u64 v[50:51], v[30:31], 0, v[44:45]
	v_lshl_add_u64 v[52:53], v[30:31], 0, v[46:47]
	v_lshl_add_u64 v[54:55], v[30:31], 0, v[48:49]
	global_load_dword v20, v[20:21], off
	s_nop 0
	global_load_dword v21, v[22:23], off
	s_nop 0
	global_load_dword v22, v[24:25], off
	global_load_dword v23, v[26:27], off
	s_nop 0
	global_load_dword v24, v[32:33], off
	global_load_dword v25, v[50:51], off
	global_load_dword v26, v[52:53], off
	global_load_dword v27, v[54:55], off
	v_or_b32_e32 v32, 16, v28
	v_mov_b32_e32 v33, v29
	v_lshlrev_b64 v[50:51], 9, v[32:33]
	v_or_b32_e32 v52, 17, v28
	v_mov_b32_e32 v53, v29
	v_or_b32_e32 v54, 18, v28
	v_mov_b32_e32 v55, v29
	v_or_b32_e32 v56, 19, v28
	v_mov_b32_e32 v57, v29
	v_or_b32_e32 v58, 24, v28
	v_mov_b32_e32 v59, v29
	v_or_b32_e32 v60, 25, v28
	v_mov_b32_e32 v61, v29
	v_or_b32_e32 v62, 26, v28
	v_mov_b32_e32 v63, v29
	v_or_b32_e32 v28, 27, v28
	v_lshl_add_u64 v[32:33], v[30:31], 0, v[50:51]
	v_lshlrev_b64 v[52:53], 9, v[52:53]
	v_lshlrev_b64 v[54:55], 9, v[54:55]
	v_lshlrev_b64 v[56:57], 9, v[56:57]
	v_lshlrev_b64 v[58:59], 9, v[58:59]
	v_lshlrev_b64 v[60:61], 9, v[60:61]
	v_lshlrev_b64 v[62:63], 9, v[62:63]
	v_lshlrev_b64 v[64:65], 9, v[28:29]
	v_lshl_add_u64 v[68:69], v[30:31], 0, v[52:53]
	v_lshl_add_u64 v[70:71], v[30:31], 0, v[54:55]
	v_lshl_add_u64 v[72:73], v[30:31], 0, v[56:57]
	v_lshl_add_u64 v[74:75], v[30:31], 0, v[58:59]
	v_lshl_add_u64 v[76:77], v[30:31], 0, v[60:61]
	v_lshl_add_u64 v[78:79], v[30:31], 0, v[62:63]
	v_lshl_add_u64 v[80:81], v[30:31], 0, v[64:65]
	global_load_dword v28, v[32:33], off
	global_load_dword v29, v[68:69], off
	global_load_dword v30, v[70:71], off
	global_load_dword v31, v[72:73], off
	s_nop 0
	global_load_dword v32, v[74:75], off
	global_load_dword v33, v[76:77], off
	global_load_dword v82, v[78:79], off
	global_load_dword v83, v[80:81], off
	s_or_b32 s10, s0, 1
	s_lshl_b32 s4, s10, 7
	s_mov_b32 s5, s25
	v_lshl_add_u64 v[68:69], v[66:67], 0, s[4:5]
	v_lshl_add_u64 v[66:67], v[68:69], 0, v[34:35]
	v_lshl_add_u64 v[70:71], v[68:69], 0, v[36:37]
	v_lshl_add_u64 v[72:73], v[68:69], 0, v[38:39]
	v_lshl_add_u64 v[74:75], v[68:69], 0, v[40:41]
	v_lshl_add_u64 v[76:77], v[68:69], 0, v[42:43]
	v_lshl_add_u64 v[86:87], v[68:69], 0, v[44:45]
	v_lshl_add_u64 v[88:89], v[68:69], 0, v[46:47]
	v_lshl_add_u64 v[90:91], v[68:69], 0, v[48:49]
	global_load_dword v80, v[66:67], off
	global_load_dword v81, v[70:71], off
	global_load_dword v78, v[72:73], off
	global_load_dword v79, v[74:75], off
	s_nop 0
	global_load_dword v70, v[76:77], off
	global_load_dword v71, v[86:87], off
	global_load_dword v66, v[88:89], off
	global_load_dword v67, v[90:91], off
	v_lshl_add_u64 v[72:73], v[68:69], 0, v[50:51]
	v_lshl_add_u64 v[74:75], v[68:69], 0, v[52:53]
	v_lshl_add_u64 v[86:87], v[68:69], 0, v[54:55]
	v_lshl_add_u64 v[88:89], v[68:69], 0, v[56:57]
	v_lshl_add_u64 v[90:91], v[68:69], 0, v[58:59]
	v_lshl_add_u64 v[92:93], v[68:69], 0, v[60:61]
	v_lshl_add_u64 v[94:95], v[68:69], 0, v[62:63]
	v_lshl_add_u64 v[96:97], v[68:69], 0, v[64:65]
	global_load_dword v76, v[72:73], off
	global_load_dword v77, v[74:75], off
	s_nop 0
	global_load_dword v74, v[86:87], off
	global_load_dword v75, v[88:89], off
	global_load_dword v72, v[90:91], off
	global_load_dword v73, v[92:93], off
	global_load_dword v68, v[94:95], off
	global_load_dword v69, v[96:97], off
	v_sub_u32_e32 v85, 63, v102
	v_cvt_f32_i32_e32 v85, v85
	v_sub_u32_e32 v89, 31, v102
	v_cvt_f32_i32_e32 v89, v89
	s_waitcnt vmcnt(35)
	v_lshlrev_b32_e32 v94, 16, v14
	v_mul_f32_e32 v88, v98, v85
	v_cmp_gt_f32_e32 vcc, s51, v88
	v_and_b32_e32 v95, 0xffff0000, v14
	v_mul_u32_u24_e32 v87, 0x140, v100
	v_cndmask_b32_e32 v88, 0, v187, vcc
	v_fmac_f32_e32 v88, v98, v85
	v_exp_f32_e32 v85, v88
	v_mul_f32_e32 v88, v98, v89
	v_cmp_gt_f32_e64 s[8:9], s51, v88
	v_lshl_or_b32 v87, v101, 1, v87
	v_lshlrev_b32_e32 v19, 9, v19
	v_cndmask_b32_e64 v88, 0, v187, s[8:9]
	v_fmac_f32_e32 v88, v98, v89
	v_exp_f32_e32 v89, v88
	v_cndmask_b32_e32 v88, 0, v188, vcc
	v_ldexp_f32 v88, v85, v88
	v_cndmask_b32_e64 v85, 0, v188, s[8:9]
	v_pk_mul_f32 v[94:95], v[88:89], v[94:95] op_sel_hi:[0,1]
	v_cvt_pk_bf16_f32 v14, v94, v95
	v_lshlrev_b32_e32 v94, 16, v15
	v_and_b32_e32 v95, 0xffff0000, v15
	v_pk_mul_f32 v[94:95], v[88:89], v[94:95] op_sel_hi:[0,1]
	v_cvt_pk_bf16_f32 v15, v94, v95
	v_lshlrev_b32_e32 v94, 16, v16
	v_and_b32_e32 v95, 0xffff0000, v16
	v_pk_mul_f32 v[94:95], v[88:89], v[94:95] op_sel_hi:[0,1]
	v_cvt_pk_bf16_f32 v16, v94, v95
	v_lshlrev_b32_e32 v94, 16, v17
	v_and_b32_e32 v95, 0xffff0000, v17
	v_ldexp_f32 v90, v89, v85
	v_mul_lo_u32 v85, v102, s53
	v_pk_mul_f32 v[88:89], v[88:89], v[94:95] op_sel_hi:[0,1]
	v_add3_u32 v91, 0, v84, v85
	v_cvt_pk_bf16_f32 v17, v88, v89
	s_waitcnt vmcnt(33)
	v_lshlrev_b32_e32 v88, 16, v10
	v_and_b32_e32 v89, 0xffff0000, v10
	v_pk_mul_f32 v[88:89], v[90:91], v[88:89] op_sel_hi:[0,1]
	v_cvt_pk_bf16_f32 v10, v88, v89
	v_lshlrev_b32_e32 v88, 16, v11
	v_and_b32_e32 v89, 0xffff0000, v11
	v_pk_mul_f32 v[88:89], v[90:91], v[88:89] op_sel_hi:[0,1]
	v_cvt_pk_bf16_f32 v11, v88, v89
	v_lshlrev_b32_e32 v88, 16, v12
	v_and_b32_e32 v89, 0xffff0000, v12
	v_pk_mul_f32 v[88:89], v[90:91], v[88:89] op_sel_hi:[0,1]
	s_lshl_b32 s8, s1, 12
	v_add_u32_e32 v87, 0, v87
	v_cvt_pk_bf16_f32 v12, v88, v89
	v_lshlrev_b32_e32 v88, 16, v13
	v_and_b32_e32 v89, 0xffff0000, v13
	v_add_u32_e32 v86, 0x3c0, v178
	v_or3_b32 v19, v19, s8, v99
	v_lshl_add_u32 v110, s1, 6, v87
	v_lshl_add_u32 v100, s0, 6, v87
	v_lshl_add_u32 v106, s10, 6, v87
	v_pk_mul_f32 v[88:89], v[90:91], v[88:89] op_sel_hi:[0,1]
	v_mov_b32_e32 v87, v1
	v_lshl_or_b32 v84, s0, 5, v19
	v_cvt_pk_bf16_f32 v13, v88, v89
	ds_write_b128 v91, v[14:17]
	ds_write_b128 v91, v[2:5] offset:20480
	ds_write_b128 v91, v[10:13] offset:10240
	s_waitcnt vmcnt(32)
	ds_write_b128 v91, v[6:9] offset:30720
	v_lshlrev_b64 v[2:3], 15, v[86:87]
	v_ashrrev_i32_e32 v85, 31, v84
	v_lshl_add_u64 v[2:3], s[20:21], 0, v[2:3]
	s_waitcnt vmcnt(31)
	v_cvt_pk_bf16_f32 v6, v20, s0
	v_lshl_add_u64 v[4:5], v[84:85], 1, v[2:3]
	s_waitcnt lgkmcnt(0)
	s_barrier
	global_store_short v[4:5], v6, off
	s_waitcnt vmcnt(31)
	v_cvt_pk_bf16_f32 v6, v21, s0
	global_store_short v[4:5], v6, off offset:256
	s_waitcnt vmcnt(31)
	v_cvt_pk_bf16_f32 v6, v22, s0
	global_store_short v[4:5], v6, off offset:512
	s_waitcnt vmcnt(31)
	v_cvt_pk_bf16_f32 v6, v23, s0
	global_store_short v[4:5], v6, off offset:768
	s_waitcnt vmcnt(31)
	v_cvt_pk_bf16_f32 v6, v24, s0
	global_store_short v[4:5], v6, off offset:2048
	s_waitcnt vmcnt(31)
	v_cvt_pk_bf16_f32 v6, v25, s0
	global_store_short v[4:5], v6, off offset:2304
	s_waitcnt vmcnt(31)
	v_cvt_pk_bf16_f32 v6, v26, s0
	global_store_short v[4:5], v6, off offset:2560
	s_waitcnt vmcnt(31)
	v_cvt_pk_bf16_f32 v6, v27, s0
	global_store_short v[4:5], v6, off offset:2816
	v_add_co_u32_e32 v4, vcc, s54, v4
	s_waitcnt vmcnt(31)
	v_cvt_pk_bf16_f32 v6, v28, s0
	v_addc_co_u32_e32 v5, vcc, 0, v5, vcc
	global_store_short v[4:5], v6, off
	s_waitcnt vmcnt(31)
	v_cvt_pk_bf16_f32 v6, v29, s0
	global_store_short v[4:5], v6, off offset:256
	s_waitcnt vmcnt(31)
	v_cvt_pk_bf16_f32 v6, v30, s0
	global_store_short v[4:5], v6, off offset:512
	s_waitcnt vmcnt(31)
	v_cvt_pk_bf16_f32 v6, v31, s0
	global_store_short v[4:5], v6, off offset:768
	s_waitcnt vmcnt(31)
	v_cvt_pk_bf16_f32 v6, v32, s0
	v_lshl_or_b32 v92, s10, 5, v19
	global_store_short v[4:5], v6, off offset:2048
	s_waitcnt vmcnt(31)
	v_cvt_pk_bf16_f32 v6, v33, s0
	v_ashrrev_i32_e32 v93, 31, v92
	global_store_short v[4:5], v6, off offset:2304
	s_waitcnt vmcnt(31)
	v_cvt_pk_bf16_f32 v6, v82, s0
	global_store_short v[4:5], v6, off offset:2560
	s_waitcnt vmcnt(31)
	v_cvt_pk_bf16_f32 v6, v83, s0
	v_lshl_add_u64 v[108:109], v[92:93], 1, v[2:3]
	s_waitcnt vmcnt(29)
	v_cvt_pk_bf16_f32 v2, v81, s0
	global_store_short v[4:5], v6, off offset:2816
	v_cvt_pk_bf16_f32 v4, v80, s0
	global_store_short v[108:109], v2, off offset:256
	s_waitcnt vmcnt(30)
	v_cvt_pk_bf16_f32 v2, v78, s0
	global_store_short v[108:109], v4, off
	global_store_short v[108:109], v2, off offset:512
	ds_read_b64_tr_b16 v[84:85], v110
	ds_read_b64_tr_b16 v[86:87], v110 offset:1280
	ds_read_b64_tr_b16 v[88:89], v100 offset:20480
	ds_read_b64_tr_b16 v[90:91], v100 offset:21760
	v_pk_mul_f32 v[16:17], v[18:19], v[82:83] op_sel_hi:[0,1]
	v_pk_mul_f32 v[14:15], v[18:19], v[32:33] op_sel_hi:[0,1]
	v_pk_mul_f32 v[12:13], v[18:19], v[30:31] op_sel_hi:[0,1]
	v_pk_mul_f32 v[10:11], v[18:19], v[28:29] op_sel_hi:[0,1]
	v_pk_mul_f32 v[8:9], v[18:19], v[26:27] op_sel_hi:[0,1]
	v_pk_mul_f32 v[6:7], v[18:19], v[24:25] op_sel_hi:[0,1]
	v_pk_mul_f32 v[4:5], v[18:19], v[22:23] op_sel_hi:[0,1]
	v_pk_mul_f32 v[2:3], v[18:19], v[20:21] op_sel_hi:[0,1]
	ds_read_b64_tr_b16 v[92:93], v110 offset:5120
	ds_read_b64_tr_b16 v[94:95], v110 offset:6400
	ds_read_b64_tr_b16 v[96:97], v100 offset:35840
	ds_read_b64_tr_b16 v[98:99], v100 offset:37120
	s_waitcnt lgkmcnt(4)
	v_mfma_f32_32x32x16_bf16 v[2:17], v[84:87], v[88:91], v[2:17]
	ds_read_b64_tr_b16 v[88:89], v106 offset:20480
	ds_read_b64_tr_b16 v[90:91], v106 offset:21760
	s_waitcnt vmcnt(19)
	v_mul_f32_e64 v32, v18, v68
	v_mul_f32_e64 v33, v18, v69
	v_pk_mul_f32 v[30:31], v[18:19], v[72:73] op_sel_hi:[0,1]
	v_pk_mul_f32 v[28:29], v[18:19], v[74:75] op_sel_hi:[0,1]
	v_pk_mul_f32 v[26:27], v[18:19], v[76:77] op_sel_hi:[0,1]
	v_pk_mul_f32 v[24:25], v[18:19], v[66:67] op_sel_hi:[0,1]
	v_pk_mul_f32 v[22:23], v[18:19], v[70:71] op_sel_hi:[0,1]
	v_pk_mul_f32 v[20:21], v[18:19], v[78:79] op_sel_hi:[0,1]
	v_pk_mul_f32 v[18:19], v[18:19], v[80:81] op_sel_hi:[0,1]
	ds_read_b64_tr_b16 v[80:81], v106 offset:35840
	ds_read_b64_tr_b16 v[82:83], v106 offset:37120
	s_waitcnt lgkmcnt(2)
	v_mfma_f32_32x32x16_bf16 v[18:33], v[84:87], v[88:91], v[18:33]
	ds_read_b64_tr_b16 v[84:85], v100 offset:25600
	ds_read_b64_tr_b16 v[86:87], v100 offset:26880
	v_cvt_pk_bf16_f32 v78, v79, s0
	global_store_short v[108:109], v78, off offset:768
	v_cvt_pk_bf16_f32 v70, v70, s0
	ds_read_b64_tr_b16 v[88:89], v100 offset:30720
	ds_read_b64_tr_b16 v[90:91], v100 offset:32000
	global_store_short v[108:109], v70, off offset:2048
	v_cvt_pk_bf16_f32 v70, v71, s0
	s_waitcnt lgkmcnt(2)
	v_mfma_f32_32x32x16_bf16 v[2:17], v[92:95], v[84:87], v[2:17]
	ds_read_b64_tr_b16 v[84:85], v106 offset:25600
	ds_read_b64_tr_b16 v[86:87], v106 offset:26880
	ds_read_b64_tr_b16 v[100:101], v110 offset:10240
	ds_read_b64_tr_b16 v[102:103], v110 offset:11520
	ds_read_b64_tr_b16 v[104:105], v106 offset:30720
	ds_read_b64_tr_b16 v[106:107], v106 offset:32000
	v_cvt_pk_bf16_f32 v66, v66, s0
	global_store_short v[108:109], v70, off offset:2304
	global_store_short v[108:109], v66, off offset:2560
	v_cvt_pk_bf16_f32 v66, v67, s0
	v_cvt_pk_bf16_f32 v70, v76, s0
	v_cvt_pk_bf16_f32 v68, v68, s0
	s_waitcnt lgkmcnt(2)
	v_mfma_f32_32x32x16_bf16 v[2:17], v[100:103], v[88:91], v[2:17]
	v_mfma_f32_32x32x16_bf16 v[18:33], v[92:95], v[84:87], v[18:33]
	ds_read_b64_tr_b16 v[84:85], v110 offset:15360
	ds_read_b64_tr_b16 v[86:87], v110 offset:16640
	global_store_short v[108:109], v66, off offset:2816
	v_add_co_u32_e32 v66, vcc, s54, v108
	s_nop 1
	v_addc_co_u32_e32 v67, vcc, 0, v109, vcc
	global_store_short v[66:67], v70, off
	v_cvt_pk_bf16_f32 v70, v77, s0
	s_waitcnt lgkmcnt(0)
	v_mfma_f32_32x32x16_bf16 v[2:17], v[84:87], v[96:99], v[2:17]
	global_store_short v[66:67], v70, off offset:256
	v_cvt_pk_bf16_f32 v70, v74, s0
	global_store_short v[66:67], v70, off offset:512
	v_cvt_pk_bf16_f32 v70, v75, s0
	global_store_short v[66:67], v70, off offset:768
	v_cvt_pk_bf16_f32 v70, v72, s0
	global_store_short v[66:67], v70, off offset:2048
	v_cvt_pk_bf16_f32 v70, v73, s0
	global_store_short v[66:67], v68, off offset:2560
	v_cvt_pk_bf16_f32 v68, v69, s0
	global_store_short v[66:67], v70, off offset:2304
	global_store_short v[66:67], v68, off offset:2816
	v_lshl_add_u64 v[66:67], s[22:23], 0, v[0:1]
	v_lshl_add_u64 v[68:69], v[66:67], 0, s[24:25]
	v_lshl_add_u64 v[70:71], v[68:69], 0, v[34:35]
	s_barrier
	global_store_dword v[70:71], v2, off
	v_lshl_add_u64 v[70:71], v[68:69], 0, v[36:37]
	v_mfma_f32_32x32x16_bf16 v[18:33], v[100:103], v[104:107], v[18:33]
	global_store_dword v[70:71], v3, off
	v_lshl_add_u64 v[2:3], v[68:69], 0, v[38:39]
	global_store_dword v[2:3], v4, off
	v_lshl_add_u64 v[2:3], v[68:69], 0, v[40:41]
	global_store_dword v[2:3], v5, off
	v_lshl_add_u64 v[2:3], v[68:69], 0, v[42:43]
	global_store_dword v[2:3], v6, off
	v_lshl_add_u64 v[2:3], v[68:69], 0, v[44:45]
	global_store_dword v[2:3], v7, off
	v_lshl_add_u64 v[2:3], v[68:69], 0, v[46:47]
	global_store_dword v[2:3], v8, off
	v_lshl_add_u64 v[2:3], v[68:69], 0, v[48:49]
	global_store_dword v[2:3], v9, off
	v_lshl_add_u64 v[2:3], v[68:69], 0, v[50:51]
	global_store_dword v[2:3], v10, off
	v_lshl_add_u64 v[2:3], v[68:69], 0, v[52:53]
	v_mfma_f32_32x32x16_bf16 v[18:33], v[84:87], v[80:83], v[18:33]
	global_store_dword v[2:3], v11, off
	v_lshl_add_u64 v[2:3], v[68:69], 0, v[54:55]
	global_store_dword v[2:3], v12, off
	v_lshl_add_u64 v[2:3], v[68:69], 0, v[56:57]
	global_store_dword v[2:3], v13, off
	v_lshl_add_u64 v[2:3], v[68:69], 0, v[58:59]
	global_store_dword v[2:3], v14, off
	v_lshl_add_u64 v[2:3], v[68:69], 0, v[60:61]
	global_store_dword v[2:3], v15, off
	v_lshl_add_u64 v[2:3], v[68:69], 0, v[62:63]
	global_store_dword v[2:3], v16, off
	v_lshl_add_u64 v[2:3], v[68:69], 0, v[64:65]
	global_store_dword v[2:3], v17, off
	v_lshl_add_u64 v[2:3], v[66:67], 0, s[4:5]
	v_lshl_add_u64 v[4:5], v[2:3], 0, v[34:35]
	global_store_dword v[4:5], v18, off
	v_lshl_add_u64 v[4:5], v[2:3], 0, v[36:37]
	global_store_dword v[4:5], v19, off
	v_lshl_add_u64 v[4:5], v[2:3], 0, v[38:39]
	global_store_dword v[4:5], v20, off
	v_lshl_add_u64 v[4:5], v[2:3], 0, v[40:41]
	global_store_dword v[4:5], v21, off
	v_lshl_add_u64 v[4:5], v[2:3], 0, v[42:43]
	global_store_dword v[4:5], v22, off
	v_lshl_add_u64 v[4:5], v[2:3], 0, v[44:45]
	global_store_dword v[4:5], v23, off
	v_lshl_add_u64 v[4:5], v[2:3], 0, v[46:47]
	global_store_dword v[4:5], v24, off
	v_lshl_add_u64 v[4:5], v[2:3], 0, v[48:49]
	global_store_dword v[4:5], v25, off
	v_lshl_add_u64 v[4:5], v[2:3], 0, v[50:51]
	global_store_dword v[4:5], v26, off
	v_lshl_add_u64 v[4:5], v[2:3], 0, v[52:53]
	global_store_dword v[4:5], v27, off
	v_lshl_add_u64 v[4:5], v[2:3], 0, v[54:55]
	global_store_dword v[4:5], v28, off
	v_lshl_add_u64 v[4:5], v[2:3], 0, v[56:57]
	global_store_dword v[4:5], v29, off
	v_lshl_add_u64 v[4:5], v[2:3], 0, v[58:59]
	global_store_dword v[4:5], v30, off
	v_lshl_add_u64 v[4:5], v[2:3], 0, v[60:61]
	global_store_dword v[4:5], v31, off
	v_lshl_add_u64 v[4:5], v[2:3], 0, v[62:63]
	v_lshl_add_u64 v[2:3], v[2:3], 0, v[64:65]
	global_store_dword v[4:5], v32, off
	global_store_dword v[2:3], v33, off
	s_waitcnt vmcnt(0)
	s_barrier
	s_and_saveexec_b64 s[4:5], s[6:7]
	s_cbranch_execz .Lrs_s_skip
	buffer_wbl2 sc1
	s_waitcnt vmcnt(0)
	v_readlane_b32 s0, v255, 3
	v_readlane_b32 s1, v255, 4
	v_mov_b32_e32 v0, 0
	v_mov_b32_e32 v2, 1
	s_nop 4
	global_atomic_add v0, v2, s[0:1] offset:44
	s_waitcnt vmcnt(0)
.Lrs_s_skip:
	s_or_b64 exec, exec, s[4:5]
	s_mov_b64 s[4:5], 0

.LBB0_757:
	s_waitcnt vmcnt(0)
	s_waitcnt vmcnt(63) expcnt(7) lgkmcnt(15)
	s_barrier
	s_mov_b64 s[4:5], exec
	v_readlane_b32 s0, v255, 6
	v_readlane_b32 s1, v255, 7
	s_and_b64 s[0:1], s[4:5], s[0:1]
	s_mov_b64 exec, s[0:1]
	s_cbranch_execz .LBB0_809
	v_readlane_b32 s6, v255, 3
	v_readlane_b32 s7, v255, 4
	v_mov_b32_e32 v0, 0
	s_mov_b32 s8, 0
	s_nop 4
.Lp7_poll:
	global_load_dword v2, v0, s[6:7] offset:40 sc1
	s_waitcnt vmcnt(0)
	v_readfirstlane_b32 s9, v2
	s_cmp_ge_u32 s9, 32
	s_cbranch_scc0 .Lp7_again
	s_cbranch_scc1 .Lp7_acq
.Lp7_again:
	s_add_u32 s8, s8, 1
	s_cmp_gt_u32 s8, 4000
	s_cbranch_scc1 .Lp7_acq
	s_sleep 2
	s_branch .Lp7_poll
.Lp7_acq:
	buffer_inv sc1
	s_waitcnt vmcnt(0)

.LBB0_816:
	s_and_b32 s11, s11, 3
	v_cvt_f32_ubyte0_e32 v0, s11
	v_sub_f32_e32 v0, 0xc0a00000, v0
	v_cmp_gt_f32_e64 s[74:75], s33, v0
	s_and_b64 s[12:13], s[74:75], exec
	s_cselect_b32 s12, 0xffffffc0, 0
	s_add_i32 s9, s9, s14
	s_cmpk_gt_i32 s9, 0x81f
	s_cselect_b64 s[76:77], -1, 0
	v_add_u32_e32 v1, v124, v131
	s_and_b64 vcc, exec, s[76:77]
	s_waitcnt vmcnt(0)
	ds_write_b128 v1, v[60:63]
	ds_write_b128 v1, v[52:55] offset:17408
	ds_write_b128 v166, v[64:67] offset:34816
	ds_write_b128 v167, v[48:51]
	ds_write_b128 v167, v[56:59] offset:17408
	ds_write_b128 v168, v[68:71] offset:34816
	ds_write_b128 v166, v[40:43] offset:55296
	ds_write_b128 v168, v[44:47] offset:55296
	ds_write_b128 v169, v[32:35] offset:55296
	ds_write_b128 v170, v[36:39] offset:55296
	s_waitcnt lgkmcnt(0)
	s_barrier
	s_cbranch_vccnz .LBB0_822
	s_cmpk_gt_i32 s9, 0x7ff
	s_mov_b64 vcc, -1
	s_cbranch_scc0 .LBB0_819
	v_readlane_b32 vcc_lo, v255, 3
	s_nop 1
	v_mov_b32_e32 v186, vcc_lo
	v_readlane_b32 vcc_lo, v255, 4
	s_nop 1
	v_mov_b32_e32 v187, vcc_lo
	s_mov_b32 s32, 0
	s_nop 1
.Lp7s_poll:
	global_load_dword v185, v[186:187], off offset:44 sc1
	s_waitcnt vmcnt(0)
	v_readfirstlane_b32 vcc_lo, v185
	s_cmp_ge_u32 vcc_lo, 32
	s_cbranch_scc1 .Lp7s_acq
	s_add_u32 s32, s32, 1
	s_cmp_gt_u32 s32, 4000
	s_cbranch_scc1 .Lp7s_acq
	s_sleep 2
	s_branch .Lp7s_poll
.Lp7s_acq:
	buffer_inv sc1
	s_waitcnt vmcnt(0)
	s_add_i32 s13, s82, s83
	s_and_b32 s13, s13, 0x7fffffc0
	s_mov_b64 vcc, 0
